# speedup vs baseline: 1.0226x; 1.0021x over previous
; #define PG8_STAGE(bufoff, gbase, voff) do { _Pragma("unroll") for (int _i = 0; _i < 2; ++_i) \
;         __builtin_amdgcn_global_load_lds((const unsigned*)((const char*)(gbase) + (voff)[_i]), (LAS unsigned*)(lds + (bufoff) + ldsw + _i * 8192), 16, 0, 0); } while (0)
; #define PG8_LDA(dst, b, h) do { _Pragma("unroll") for (int m = 0; m < 4; ++m) _Pragma("unroll") for (int k = 0; k < 2; ++k) dst[m][k] = *(const LAS bf16x8*)(lds + PG8_SA(b, h) + aoff + m * 2048 + k * 1024); } while (0)
; #define PG8_LDB(dst, b, h) do { _Pragma("unroll") for (int n = 0; n < 2; ++n) _Pragma("unroll") for (int k = 0; k < 2; ++k) dst[n][k] = *(const LAS bf16x8*)(lds + PG8_SB(b, h) + boff + n * 2048 + k * 1024); } while (0)
; #define PG8_MMA(ai, bj, At, Bt) do { __builtin_amdgcn_s_setprio(1); _Pragma("unroll") for (int m = 0; m < 4; ++m) _Pragma("unroll") for (int n = 0; n < 2; ++n) _Pragma("unroll") for (int k = 0; k < 2; ++k) \
;         acc[ai][bj][m][n] = __builtin_amdgcn_mfma_f32_16x16x32_bf16(Bt[n][k], At[m][k], acc[ai][bj][m][n], 0, 0, 0); __builtin_amdgcn_s_setprio(0); } while (0)
; #define PG8_BAR __builtin_amdgcn_s_barrier()
; template <class Epi>
; __device__ __forceinline__ void gemm_phase(const int tid, LAS unsigned char* lds, const Gemm g, const StaticOrder& S, const Epi& E) {
;     ...
;             PG8_LDB(B0, 0, 0); PG8_SCHED; PG8_LDA(At, 0, 0);
;             PG8_WAIT_L(8); PG8_BAR; PG8_WAIT_L(0); PG8_MMA(0, 0, At, B0); PG8_BAR; PG8_SCHED;
;             PG8_LDB(B1, 0, 1); PG8_STAGE(PG8_SB(0, 0), b2, voffB);
;             PG8_BAR; PG8_WAIT_L(0); PG8_MMA(0, 1, At, B1); PG8_BAR;
;             PG8_LDA(At, 0, 1); PG8_STAGE(PG8_SA(0, 0), a2, voffA);
;             PG8_BAR; PG8_WAIT_L(0); PG8_MMA(1, 0, At, B0); PG8_BAR; PG8_SCHED;
;             PG8_STAGE(PG8_SB(0, 1), b2 + hstep, voffB);
;             { const int first_ = __builtin_amdgcn_readfirstlane((ui > 0 && t == 0) ? 1 : 0);
;               if constexpr (Epi::SMIN == 8) asm volatile("s_cmp_eq_u32 %0, 0\n\ts_cbranch_scc1 .Lws_a%=\n\ts_waitcnt vmcnt(14)\n\ts_branch .Lws_b%=\n.Lws_a%=:\n\ts_waitcnt vmcnt(6)\n.Lws_b%=:" :: "s"(first_) : "memory", "scc");
;               else if constexpr (Epi::SMIN == 24) asm volatile("s_cmp_eq_u32 %0, 0\n\ts_cbranch_scc1 .Lws_a%=\n\ts_waitcnt vmcnt(30)\n\ts_branch .Lws_b%=\n.Lws_a%=:\n\ts_waitcnt vmcnt(6)\n.Lws_b%=:" :: "s"(first_) : "memory", "scc");
;               else PG8_WAIT_V(6); }
.LBB0_419:
	s_add_i32 s68, 0, 0x10000
	v_add_u32_e32 v134, s68, v246
	ds_read_b128 v[106:109], v134
	ds_read_b128 v[110:113], v134 offset:1024
	ds_read_b128 v[122:125], v134 offset:2048
	ds_read_b128 v[134:137], v134 offset:3072
	s_add_i32 s67, s66, 2
	s_cmp_eq_u32 s54, s66
	s_cselect_b32 s15, s9, s61
	s_cselect_b32 s14, s8, s60
	s_cselect_b32 s17, s11, s65
	s_cselect_b32 s16, s10, s64
	ds_read_b128 v[138:141], v248
	ds_read_b128 v[142:145], v248 offset:1024
	ds_read_b128 v[146:149], v248 offset:2048
	ds_read_b128 v[150:153], v248 offset:3072
	ds_read_b128 v[154:157], v248 offset:4096
	ds_read_b128 v[158:161], v248 offset:5120
	ds_read_b128 v[162:165], v248 offset:6144
	ds_read_b128 v[174:177], v248 offset:7168
	s_waitcnt lgkmcnt(8)
	s_barrier
	s_setprio 1
	s_waitcnt lgkmcnt(7)
	v_mfma_f32_16x16x32_bf16 v[170:173], v[106:109], v[138:141], v[170:173]
	v_mfma_f32_16x16x32_bf16 v[166:169], v[122:125], v[138:141], v[166:169]
	s_waitcnt lgkmcnt(5)
	v_mfma_f32_16x16x32_bf16 v[118:121], v[106:109], v[146:149], v[118:121]
	v_mfma_f32_16x16x32_bf16 v[114:117], v[122:125], v[146:149], v[114:117]
	s_waitcnt lgkmcnt(3)
	v_mfma_f32_16x16x32_bf16 v[94:97], v[106:109], v[154:157], v[94:97]
	v_mfma_f32_16x16x32_bf16 v[90:93], v[122:125], v[154:157], v[90:93]
	s_waitcnt lgkmcnt(1)
	v_mfma_f32_16x16x32_bf16 v[78:81], v[106:109], v[162:165], v[78:81]
	v_mfma_f32_16x16x32_bf16 v[74:77], v[122:125], v[162:165], v[74:77]
	v_mfma_f32_16x16x32_bf16 v[170:173], v[110:113], v[142:145], v[170:173]
	v_mfma_f32_16x16x32_bf16 v[166:169], v[134:137], v[142:145], v[166:169]
	v_mfma_f32_16x16x32_bf16 v[118:121], v[110:113], v[150:153], v[118:121]
	v_mfma_f32_16x16x32_bf16 v[114:117], v[134:137], v[150:153], v[114:117]
	v_mfma_f32_16x16x32_bf16 v[94:97], v[110:113], v[158:161], v[94:97]
	v_mfma_f32_16x16x32_bf16 v[90:93], v[134:137], v[158:161], v[90:93]
	s_waitcnt lgkmcnt(0)
	v_mfma_f32_16x16x32_bf16 v[78:81], v[110:113], v[174:177], v[78:81]
	v_mfma_f32_16x16x32_bf16 v[74:77], v[134:137], v[174:177], v[74:77]
	s_setprio 0
	s_barrier
	s_add_i32 s69, 0, 0x14000
	s_add_i32 s68, s68, s28
	v_add_u32_e32 v190, s69, v246
	s_mov_b32 m0, s68
	ds_read_b128 v[178:181], v190
	ds_read_b128 v[182:185], v190 offset:1024
	ds_read_b128 v[186:189], v190 offset:2048
	ds_read_b128 v[190:193], v190 offset:3072
	global_load_lds_dwordx4 v0, s[16:17]
	s_add_i32 m0, s68, 0x2000
	s_nop 0
	global_load_lds_dwordx4 v194, s[16:17]
	s_barrier
	s_setprio 1
	s_waitcnt lgkmcnt(3)
	v_mfma_f32_16x16x32_bf16 v[130:133], v[178:181], v[138:141], v[130:133]
	s_waitcnt lgkmcnt(1)
	v_mfma_f32_16x16x32_bf16 v[126:129], v[186:189], v[138:141], v[126:129]
	v_mfma_f32_16x16x32_bf16 v[102:105], v[178:181], v[146:149], v[102:105]
	v_mfma_f32_16x16x32_bf16 v[98:101], v[186:189], v[146:149], v[98:101]
	v_mfma_f32_16x16x32_bf16 v[86:89], v[178:181], v[154:157], v[86:89]
	v_mfma_f32_16x16x32_bf16 v[82:85], v[186:189], v[154:157], v[82:85]
	v_mfma_f32_16x16x32_bf16 v[70:73], v[178:181], v[162:165], v[70:73]
	v_mfma_f32_16x16x32_bf16 v[66:69], v[186:189], v[162:165], v[66:69]
	v_mfma_f32_16x16x32_bf16 v[130:133], v[182:185], v[142:145], v[130:133]
	s_waitcnt lgkmcnt(0)
	v_mfma_f32_16x16x32_bf16 v[126:129], v[190:193], v[142:145], v[126:129]
	v_mfma_f32_16x16x32_bf16 v[102:105], v[182:185], v[150:153], v[102:105]
	v_mfma_f32_16x16x32_bf16 v[98:101], v[190:193], v[150:153], v[98:101]
	v_mfma_f32_16x16x32_bf16 v[86:89], v[182:185], v[158:161], v[86:89]
	v_mfma_f32_16x16x32_bf16 v[82:85], v[190:193], v[158:161], v[82:85]
	v_mfma_f32_16x16x32_bf16 v[70:73], v[182:185], v[174:177], v[70:73]
	v_mfma_f32_16x16x32_bf16 v[66:69], v[190:193], v[174:177], v[66:69]
	s_setprio 0
	s_mov_b32 m0, s36
	s_barrier
	ds_read_b128 v[138:141], v248 offset:16384
	ds_read_b128 v[142:145], v248 offset:17408
	ds_read_b128 v[146:149], v248 offset:18432
	ds_read_b128 v[150:153], v248 offset:19456
	ds_read_b128 v[154:157], v248 offset:20480
	ds_read_b128 v[158:161], v248 offset:21504
	ds_read_b128 v[162:165], v248 offset:22528
	ds_read_b128 v[174:177], v248 offset:23552
	global_load_lds_dwordx4 v198, s[14:15]
	s_mov_b32 m0, s37
	s_nop 0
	global_load_lds_dwordx4 v196, s[14:15]
	s_barrier
	s_setprio 1
	s_waitcnt lgkmcnt(7)
	v_mfma_f32_16x16x32_bf16 v[62:65], v[106:109], v[138:141], v[62:65]
	v_mfma_f32_16x16x32_bf16 v[58:61], v[122:125], v[138:141], v[58:61]
	s_waitcnt lgkmcnt(5)
	v_mfma_f32_16x16x32_bf16 v[46:49], v[106:109], v[146:149], v[46:49]
	v_mfma_f32_16x16x32_bf16 v[42:45], v[122:125], v[146:149], v[42:45]
	s_waitcnt lgkmcnt(3)
	v_mfma_f32_16x16x32_bf16 v[30:33], v[106:109], v[154:157], v[30:33]
	v_mfma_f32_16x16x32_bf16 v[26:29], v[122:125], v[154:157], v[26:29]
	s_waitcnt lgkmcnt(1)
	v_mfma_f32_16x16x32_bf16 v[14:17], v[106:109], v[162:165], v[14:17]
	v_mfma_f32_16x16x32_bf16 v[10:13], v[122:125], v[162:165], v[10:13]
	v_mfma_f32_16x16x32_bf16 v[62:65], v[110:113], v[142:145], v[62:65]
	v_mfma_f32_16x16x32_bf16 v[58:61], v[134:137], v[142:145], v[58:61]
	v_mfma_f32_16x16x32_bf16 v[46:49], v[110:113], v[150:153], v[46:49]
	v_mfma_f32_16x16x32_bf16 v[42:45], v[134:137], v[150:153], v[42:45]
	v_mfma_f32_16x16x32_bf16 v[30:33], v[110:113], v[158:161], v[30:33]
	v_mfma_f32_16x16x32_bf16 v[26:29], v[134:137], v[158:161], v[26:29]
	s_waitcnt lgkmcnt(0)
	v_mfma_f32_16x16x32_bf16 v[14:17], v[110:113], v[174:177], v[14:17]
	v_mfma_f32_16x16x32_bf16 v[10:13], v[134:137], v[174:177], v[10:13]
	s_setprio 0
	s_barrier
	s_add_u32 s16, s16, s26
	s_addc_u32 s17, s17, 0
	s_add_i32 s68, s69, s28
	s_mov_b32 m0, s68
	s_nop 0
	global_load_lds_dwordx4 v0, s[16:17]
	s_add_i32 m0, s68, 0x2000
	s_cmp_eq_u32 s66, 0
	global_load_lds_dwordx4 v194, s[16:17]
	s_cselect_b64 s[16:17], -1, 0
	s_and_b64 s[16:17], s[12:13], s[16:17]
	v_cndmask_b32_e64 v106, 0, 1, s[16:17]
	s_nop 0
	v_readfirstlane_b32 s16, v106
	s_and_b32 s16, s16, 1
	s_cmp_eq_u32 s16, 0
	s_cbranch_scc1 .Lws_a0
	s_waitcnt vmcnt(30)
	s_branch .Lws_b0

; #define PG8_STAGE(bufoff, gbase, voff) do { _Pragma("unroll") for (int _i = 0; _i < 2; ++_i) \
;         __builtin_amdgcn_global_load_lds((const unsigned*)((const char*)(gbase) + (voff)[_i]), (LAS unsigned*)(lds + (bufoff) + ldsw + _i * 8192), 16, 0, 0); } while (0)
; #define PG8_LDA(dst, b, h) do { _Pragma("unroll") for (int m = 0; m < 4; ++m) _Pragma("unroll") for (int k = 0; k < 2; ++k) dst[m][k] = *(const LAS bf16x8*)(lds + PG8_SA(b, h) + aoff + m * 2048 + k * 1024); } while (0)
; #define PG8_LDB(dst, b, h) do { _Pragma("unroll") for (int n = 0; n < 2; ++n) _Pragma("unroll") for (int k = 0; k < 2; ++k) dst[n][k] = *(const LAS bf16x8*)(lds + PG8_SB(b, h) + boff + n * 2048 + k * 1024); } while (0)
; #define PG8_MMA(ai, bj, At, Bt) do { __builtin_amdgcn_s_setprio(1); _Pragma("unroll") for (int m = 0; m < 4; ++m) _Pragma("unroll") for (int n = 0; n < 2; ++n) _Pragma("unroll") for (int k = 0; k < 2; ++k) \
;         acc[ai][bj][m][n] = __builtin_amdgcn_mfma_f32_16x16x32_bf16(Bt[n][k], At[m][k], acc[ai][bj][m][n], 0, 0, 0); __builtin_amdgcn_s_setprio(0); } while (0)
; #define PG8_WAIT_L(n) asm volatile("s_waitcnt lgkmcnt(" #n ")" ::: "memory")
; #define PG8_BAR __builtin_amdgcn_s_barrier()
; #define PG8_SCHED __builtin_amdgcn_sched_barrier(0)
; template <class Epi>
; __device__ __forceinline__ void gemm_phase(const int tid, LAS unsigned char* lds, const Gemm g, const StaticOrder& S, const Epi& E) {
;     ...
;             PG8_BAR; PG8_MMA(1, 1, At, B1); PG8_BAR;
;             PG8_LDB(B0, 1, 0); PG8_SCHED; PG8_LDA(At, 1, 0); PG8_STAGE(PG8_SA(0, 1), a2 + hstep, voffA);
;             PG8_WAIT_L(8); PG8_BAR; PG8_WAIT_L(0); PG8_MMA(0, 0, At, B0); PG8_BAR; PG8_SCHED;
;             PG8_LDB(B1, 1, 1); PG8_STAGE(PG8_SB(1, 0), b3, voffB);
;             PG8_BAR; PG8_WAIT_L(0); PG8_MMA(0, 1, At, B1); PG8_BAR;
;             PG8_LDA(At, 1, 1); PG8_STAGE(PG8_SA(1, 0), a3, voffA);
.Lws_b0:
	s_barrier
	s_setprio 1
	v_mfma_f32_16x16x32_bf16 v[54:57], v[178:181], v[138:141], v[54:57]
	v_mfma_f32_16x16x32_bf16 v[50:53], v[186:189], v[138:141], v[50:53]
	v_mfma_f32_16x16x32_bf16 v[38:41], v[178:181], v[146:149], v[38:41]
	v_mfma_f32_16x16x32_bf16 v[34:37], v[186:189], v[146:149], v[34:37]
	v_mfma_f32_16x16x32_bf16 v[22:25], v[178:181], v[154:157], v[22:25]
	v_mfma_f32_16x16x32_bf16 v[18:21], v[186:189], v[154:157], v[18:21]
	v_mfma_f32_16x16x32_bf16 v[6:9], v[178:181], v[162:165], v[6:9]
	v_mfma_f32_16x16x32_bf16 v[2:5], v[186:189], v[162:165], v[2:5]
	v_mfma_f32_16x16x32_bf16 v[54:57], v[182:185], v[142:145], v[54:57]
	v_mfma_f32_16x16x32_bf16 v[50:53], v[190:193], v[142:145], v[50:53]
	v_mfma_f32_16x16x32_bf16 v[38:41], v[182:185], v[150:153], v[38:41]
	v_mfma_f32_16x16x32_bf16 v[34:37], v[190:193], v[150:153], v[34:37]
	v_mfma_f32_16x16x32_bf16 v[22:25], v[182:185], v[158:161], v[22:25]
	v_mfma_f32_16x16x32_bf16 v[18:21], v[190:193], v[158:161], v[18:21]
	v_mfma_f32_16x16x32_bf16 v[6:9], v[182:185], v[174:177], v[6:9]
	v_mfma_f32_16x16x32_bf16 v[2:5], v[190:193], v[174:177], v[2:5]
	s_setprio 0
	s_add_i32 s16, 0, 0x18000
	v_add_u32_e32 v134, s16, v246
	s_barrier
	ds_read_b128 v[106:109], v134
	ds_read_b128 v[110:113], v134 offset:1024
	ds_read_b128 v[122:125], v134 offset:2048
	ds_read_b128 v[134:137], v134 offset:3072
	s_add_u32 s14, s14, s26
	s_addc_u32 s15, s15, 0
	s_mov_b32 m0, s38
	ds_read_b128 v[138:141], v248 offset:32768
	ds_read_b128 v[142:145], v248 offset:33792
	ds_read_b128 v[146:149], v248 offset:34816
	ds_read_b128 v[150:153], v248 offset:35840
	ds_read_b128 v[154:157], v248 offset:36864
	ds_read_b128 v[158:161], v248 offset:37888
	ds_read_b128 v[162:165], v248 offset:38912
	ds_read_b128 v[174:177], v248 offset:39936
	global_load_lds_dwordx4 v198, s[14:15]
	s_mov_b32 m0, s39
	s_nop 0
	global_load_lds_dwordx4 v196, s[14:15]
	s_waitcnt lgkmcnt(8)
	s_barrier
	s_setprio 1
	s_waitcnt lgkmcnt(7)
	v_mfma_f32_16x16x32_bf16 v[170:173], v[106:109], v[138:141], v[170:173]
	v_mfma_f32_16x16x32_bf16 v[166:169], v[122:125], v[138:141], v[166:169]
	s_waitcnt lgkmcnt(5)
	v_mfma_f32_16x16x32_bf16 v[118:121], v[106:109], v[146:149], v[118:121]
	v_mfma_f32_16x16x32_bf16 v[114:117], v[122:125], v[146:149], v[114:117]
	s_waitcnt lgkmcnt(3)
	v_mfma_f32_16x16x32_bf16 v[94:97], v[106:109], v[154:157], v[94:97]
	v_mfma_f32_16x16x32_bf16 v[90:93], v[122:125], v[154:157], v[90:93]
	s_waitcnt lgkmcnt(1)
	v_mfma_f32_16x16x32_bf16 v[78:81], v[106:109], v[162:165], v[78:81]
	v_mfma_f32_16x16x32_bf16 v[74:77], v[122:125], v[162:165], v[74:77]
	v_mfma_f32_16x16x32_bf16 v[170:173], v[110:113], v[142:145], v[170:173]
	v_mfma_f32_16x16x32_bf16 v[166:169], v[134:137], v[142:145], v[166:169]
	v_mfma_f32_16x16x32_bf16 v[118:121], v[110:113], v[150:153], v[118:121]
	v_mfma_f32_16x16x32_bf16 v[114:117], v[134:137], v[150:153], v[114:117]
	v_mfma_f32_16x16x32_bf16 v[94:97], v[110:113], v[158:161], v[94:97]
	v_mfma_f32_16x16x32_bf16 v[90:93], v[134:137], v[158:161], v[90:93]
	s_waitcnt lgkmcnt(0)
	v_mfma_f32_16x16x32_bf16 v[78:81], v[110:113], v[174:177], v[78:81]
	v_mfma_f32_16x16x32_bf16 v[74:77], v[134:137], v[174:177], v[74:77]
	s_setprio 0
	s_barrier
	s_add_i32 s14, 0, 0x1c000
	s_add_i32 s15, s16, s28
	v_add_u32_e32 v190, s14, v246
	s_cmp_eq_u32 s54, s66
	s_cselect_b32 s17, s11, s65
	s_cselect_b32 s16, s10, s64
	s_cselect_b32 s69, s9, s61
	s_cselect_b32 s68, s8, s60
	s_add_i32 m0, s15, 0xffffff80
	ds_read_b128 v[178:181], v190
	ds_read_b128 v[182:185], v190 offset:1024
	ds_read_b128 v[186:189], v190 offset:2048
	ds_read_b128 v[190:193], v190 offset:3072
	global_load_lds_dwordx4 v0, s[16:17] offset:128
	s_add_i32 m0, s15, 0x1f80
	s_nop 0
	global_load_lds_dwordx4 v194, s[16:17] offset:128
	s_barrier
	s_setprio 1
	s_waitcnt lgkmcnt(3)
	v_mfma_f32_16x16x32_bf16 v[130:133], v[178:181], v[138:141], v[130:133]
	s_waitcnt lgkmcnt(1)
	v_mfma_f32_16x16x32_bf16 v[126:129], v[186:189], v[138:141], v[126:129]
	v_mfma_f32_16x16x32_bf16 v[102:105], v[178:181], v[146:149], v[102:105]
	v_mfma_f32_16x16x32_bf16 v[98:101], v[186:189], v[146:149], v[98:101]
	v_mfma_f32_16x16x32_bf16 v[86:89], v[178:181], v[154:157], v[86:89]
	v_mfma_f32_16x16x32_bf16 v[82:85], v[186:189], v[154:157], v[82:85]
	v_mfma_f32_16x16x32_bf16 v[70:73], v[178:181], v[162:165], v[70:73]
	v_mfma_f32_16x16x32_bf16 v[66:69], v[186:189], v[162:165], v[66:69]
	v_mfma_f32_16x16x32_bf16 v[130:133], v[182:185], v[142:145], v[130:133]
	s_waitcnt lgkmcnt(0)
	v_mfma_f32_16x16x32_bf16 v[126:129], v[190:193], v[142:145], v[126:129]
	v_mfma_f32_16x16x32_bf16 v[102:105], v[182:185], v[150:153], v[102:105]
	v_mfma_f32_16x16x32_bf16 v[98:101], v[190:193], v[150:153], v[98:101]
	v_mfma_f32_16x16x32_bf16 v[86:89], v[182:185], v[158:161], v[86:89]
	v_mfma_f32_16x16x32_bf16 v[82:85], v[190:193], v[158:161], v[82:85]
	v_mfma_f32_16x16x32_bf16 v[70:73], v[182:185], v[174:177], v[70:73]
	v_mfma_f32_16x16x32_bf16 v[66:69], v[190:193], v[174:177], v[66:69]
	s_setprio 0
	s_add_i32 m0, s46, 0xffffff80
	s_barrier
	ds_read_b128 v[138:141], v248 offset:49152
	ds_read_b128 v[142:145], v248 offset:50176
	ds_read_b128 v[146:149], v248 offset:51200
	ds_read_b128 v[150:153], v248 offset:52224
	ds_read_b128 v[154:157], v248 offset:53248
	ds_read_b128 v[158:161], v248 offset:54272
	ds_read_b128 v[162:165], v248 offset:55296
	ds_read_b128 v[174:177], v248 offset:56320
	global_load_lds_dwordx4 v198, s[68:69] offset:128
	s_add_i32 m0, s47, 0xffffff80
	s_nop 0
	global_load_lds_dwordx4 v196, s[68:69] offset:128
	s_barrier
; #define PG8_STAGE(bufoff, gbase, voff) do { _Pragma("unroll") for (int _i = 0; _i < 2; ++_i) \
;         __builtin_amdgcn_global_load_lds((const unsigned*)((const char*)(gbase) + (voff)[_i]), (LAS unsigned*)(lds + (bufoff) + ldsw + _i * 8192), 16, 0, 0); } while (0)
; #define PG8_LDA(dst, b, h) do { _Pragma("unroll") for (int m = 0; m < 4; ++m) _Pragma("unroll") for (int k = 0; k < 2; ++k) dst[m][k] = *(const LAS bf16x8*)(lds + PG8_SA(b, h) + aoff + m * 2048 + k * 1024); } while (0)
; #define PG8_MMA(ai, bj, At, Bt) do { __builtin_amdgcn_s_setprio(1); _Pragma("unroll") for (int m = 0; m < 4; ++m) _Pragma("unroll") for (int n = 0; n < 2; ++n) _Pragma("unroll") for (int k = 0; k < 2; ++k) \
;         acc[ai][bj][m][n] = __builtin_amdgcn_mfma_f32_16x16x32_bf16(Bt[n][k], At[m][k], acc[ai][bj][m][n], 0, 0, 0); __builtin_amdgcn_s_setprio(0); } while (0)
; #define PG8_WAIT_V(n) asm volatile("s_waitcnt vmcnt(" #n ")" ::: "memory")
; #define PG8_WAIT_L(n) asm volatile("s_waitcnt lgkmcnt(" #n ")" ::: "memory")
; #define PG8_BAR __builtin_amdgcn_s_barrier()
; #define PG8_SCHED __builtin_amdgcn_sched_barrier(0)
; template <class Epi>
; __device__ __forceinline__ void gemm_phase(const int tid, LAS unsigned char* lds, const Gemm g, const StaticOrder& S, const Epi& E) {
;     ...
;             PG8_LDA(At, 1, 1); PG8_STAGE(PG8_SA(1, 0), a3, voffA);
;             PG8_BAR; PG8_WAIT_L(0); PG8_MMA(1, 0, At, B0); PG8_BAR; PG8_SCHED;
;             PG8_STAGE(PG8_SB(1, 1), b3 + hstep, voffB);
;             PG8_WAIT_V(6); PG8_BAR; PG8_STAGE(PG8_SA(1, 1), a3 + hstep, voffA);
;             PG8_MMA(1, 1, At, B1); PG8_BAR;
;         }
	s_setprio 1
	s_waitcnt lgkmcnt(7)
	v_mfma_f32_16x16x32_bf16 v[62:65], v[106:109], v[138:141], v[62:65]
	v_mfma_f32_16x16x32_bf16 v[58:61], v[122:125], v[138:141], v[58:61]
	s_waitcnt lgkmcnt(5)
	v_mfma_f32_16x16x32_bf16 v[46:49], v[106:109], v[146:149], v[46:49]
	v_mfma_f32_16x16x32_bf16 v[42:45], v[122:125], v[146:149], v[42:45]
	s_waitcnt lgkmcnt(3)
	v_mfma_f32_16x16x32_bf16 v[30:33], v[106:109], v[154:157], v[30:33]
	v_mfma_f32_16x16x32_bf16 v[26:29], v[122:125], v[154:157], v[26:29]
	s_waitcnt lgkmcnt(1)
	v_mfma_f32_16x16x32_bf16 v[14:17], v[106:109], v[162:165], v[14:17]
	v_mfma_f32_16x16x32_bf16 v[10:13], v[122:125], v[162:165], v[10:13]
	v_mfma_f32_16x16x32_bf16 v[62:65], v[110:113], v[142:145], v[62:65]
	v_mfma_f32_16x16x32_bf16 v[58:61], v[134:137], v[142:145], v[58:61]
	v_mfma_f32_16x16x32_bf16 v[46:49], v[110:113], v[150:153], v[46:49]
	v_mfma_f32_16x16x32_bf16 v[42:45], v[134:137], v[150:153], v[42:45]
	v_mfma_f32_16x16x32_bf16 v[30:33], v[110:113], v[158:161], v[30:33]
	v_mfma_f32_16x16x32_bf16 v[26:29], v[134:137], v[158:161], v[26:29]
	s_waitcnt lgkmcnt(0)
	v_mfma_f32_16x16x32_bf16 v[14:17], v[110:113], v[174:177], v[14:17]
	v_mfma_f32_16x16x32_bf16 v[10:13], v[134:137], v[174:177], v[10:13]
	s_setprio 0
	s_barrier
	s_add_i32 s14, s14, s28
	s_add_u32 s16, s16, s26
	s_addc_u32 s17, s17, 0
	s_add_i32 m0, s14, 0xffffff80
	s_nop 0
	global_load_lds_dwordx4 v0, s[16:17] offset:128
	s_add_i32 m0, s14, 0x1f80
	s_nop 0
	global_load_lds_dwordx4 v194, s[16:17] offset:128
	s_add_u32 s68, s68, s26
	s_addc_u32 s69, s69, 0
	s_add_i32 m0, s48, 0xffffff80
	s_waitcnt vmcnt(6)
	s_barrier
	global_load_lds_dwordx4 v198, s[68:69] offset:128
	s_add_i32 m0, s49, 0xffffff80
	s_nop 0
	global_load_lds_dwordx4 v196, s[68:69] offset:128
	s_setprio 1
	v_mfma_f32_16x16x32_bf16 v[54:57], v[178:181], v[138:141], v[54:57]
	v_mfma_f32_16x16x32_bf16 v[50:53], v[186:189], v[138:141], v[50:53]
	v_mfma_f32_16x16x32_bf16 v[38:41], v[178:181], v[146:149], v[38:41]
	v_mfma_f32_16x16x32_bf16 v[34:37], v[186:189], v[146:149], v[34:37]
	v_mfma_f32_16x16x32_bf16 v[22:25], v[178:181], v[154:157], v[22:25]
	v_mfma_f32_16x16x32_bf16 v[18:21], v[186:189], v[154:157], v[18:21]
	v_mfma_f32_16x16x32_bf16 v[6:9], v[178:181], v[162:165], v[6:9]
	v_mfma_f32_16x16x32_bf16 v[2:5], v[186:189], v[162:165], v[2:5]
	v_mfma_f32_16x16x32_bf16 v[54:57], v[182:185], v[142:145], v[54:57]
	v_mfma_f32_16x16x32_bf16 v[50:53], v[190:193], v[142:145], v[50:53]
	v_mfma_f32_16x16x32_bf16 v[38:41], v[182:185], v[150:153], v[38:41]
	v_mfma_f32_16x16x32_bf16 v[34:37], v[190:193], v[150:153], v[34:37]
	v_mfma_f32_16x16x32_bf16 v[22:25], v[182:185], v[158:161], v[22:25]
	v_mfma_f32_16x16x32_bf16 v[18:21], v[190:193], v[158:161], v[18:21]
	v_mfma_f32_16x16x32_bf16 v[6:9], v[182:185], v[174:177], v[6:9]
	v_mfma_f32_16x16x32_bf16 v[2:5], v[190:193], v[174:177], v[2:5]
	s_setprio 0
	s_add_u32 s60, s60, 0x100
	s_addc_u32 s61, s61, 0
	s_add_u32 s64, s64, 0x100
	s_addc_u32 s65, s65, 0
	s_cmp_ge_u32 s67, s51
	s_mov_b32 s66, s67
	s_barrier
	s_cbranch_scc0 .LBB0_419
; __device__ __forceinline__ unsigned cvtpk(float lo, float hi) { unsigned r; asm volatile("v_cvt_pk_bf16_f32 %0, %1, %2" : "=v"(r) : "v"(lo), "v"(hi)); return r; }
; __device__ __forceinline__ float bflo(unsigned w) { return __uint_as_float(w << 16); }
; __device__ __forceinline__ float bfhi(unsigned w) { return __uint_as_float(w & 0xffff0000u); }
;     __device__ __forceinline__ void operator()(const AccT& acc, const pg8::Unit& u, int wr, int wc, int fr, int fq, pg8::RsCache& rsc) const {
;         const int row0 = u.pm * 256 + wr * 64 + fr, col0 = u.pn * 256 + wc * 32 + 8 * fq;
;         u32x4 xv[2][4][2];
; #pragma unroll
;         for (int ai = 0; ai < 2; ++ai)
; #pragma unroll
;             for (int m = 0; m < 4; ++m)
; #pragma unroll
;                 for (int bj = 0; bj < 2; ++bj) xv[ai][m][bj] = *(const u32x4*)(XB + (size_t)(row0 + ai * 128 + m * 16) * DM + col0 + bj * 128);
;         asm volatile("" ::: "memory");
; #pragma unroll
;         for (int ai = 0; ai < 2; ++ai) {
; #pragma unroll
;             for (int m = 0; m < 4; ++m) {
;                 const int row = row0 + ai * 128 + m * 16; float ss = 0.f;
; #pragma unroll
;                 for (int bj = 0; bj < 2; ++bj) {
;                     const u32x4 xx = xv[ai][m][bj]; const f32x4 a0 = acc[ai][bj][m][0] * scale, a1 = acc[ai][bj][m][1] * scale;
;                     const float y0 = bflo(xx.x) + a0[0], y1 = bfhi(xx.x) + a0[1], y2 = bflo(xx.y) + a0[2], y3 = bfhi(xx.y) + a0[3];
;                     const float y4 = bflo(xx.z) + a1[0], y5 = bfhi(xx.z) + a1[1], y6 = bflo(xx.w) + a1[2], y7 = bfhi(xx.w) + a1[3];
;                     u32x4 w; w.x = cvtpk(y0, y1); w.y = cvtpk(y2, y3); w.z = cvtpk(y4, y5); w.w = cvtpk(y6, y7);
;                     *(u32x4*)(XB + (size_t)row * DM + col0 + bj * 128) = w;
;                     ss += (y0 * y0 + y1 * y1) + (y2 * y2 + y3 * y3) + (y4 * y4 + y5 * y5) + (y6 * y6 + y7 * y7);
;                 }
;                 ss = xadd<16>(ss); ss = xadd<32>(ss);
;                 if (fq == 0) ssq_next[(size_t)row * 32 + u.pn * 4 + wc] = ss;
;             }
;         }
;     }
	v_lshl_or_b32 v206, s30, 8, v247
	v_lshl_add_u32 v234, s59, 8, v245
	v_ashrrev_i32_e32 v207, 31, v206
	v_lshlrev_b64 v[236:237], 1, v[206:207]
	v_ashrrev_i32_e32 v235, 31, v234
	v_lshl_add_u64 v[106:107], s[62:63], 0, v[236:237]
	v_lshlrev_b64 v[238:239], 12, v[234:235]
	v_lshl_add_u64 v[108:109], v[106:107], 0, v[238:239]
	global_load_dwordx4 v[190:193], v[108:109], off
	global_load_dwordx4 v[186:189], v[108:109], off offset:256
	v_or_b32_e32 v230, 16, v234
	v_ashrrev_i32_e32 v231, 31, v230
	v_or_b32_e32 v226, 32, v234
	v_lshlrev_b64 v[232:233], 12, v[230:231]
	v_ashrrev_i32_e32 v227, 31, v226
	v_or_b32_e32 v222, 48, v234
	v_lshl_add_u64 v[108:109], v[106:107], 0, v[232:233]
	v_lshlrev_b64 v[228:229], 12, v[226:227]
	v_ashrrev_i32_e32 v223, 31, v222
	v_add_u32_e32 v218, 0x80, v234
	global_load_dwordx4 v[182:185], v[108:109], off
	global_load_dwordx4 v[178:181], v[108:109], off offset:256
	v_lshl_add_u64 v[108:109], v[106:107], 0, v[228:229]
	v_lshlrev_b64 v[224:225], 12, v[222:223]
	v_ashrrev_i32_e32 v219, 31, v218
	v_add_u32_e32 v214, 0x90, v234
	global_load_dwordx4 v[174:177], v[108:109], off
	global_load_dwordx4 v[162:165], v[108:109], off offset:256
	v_lshl_add_u64 v[108:109], v[106:107], 0, v[224:225]
	v_lshlrev_b64 v[220:221], 12, v[218:219]
	v_ashrrev_i32_e32 v215, 31, v214
	v_add_u32_e32 v210, 0xa0, v234
	v_add_u32_e32 v204, 0xb0, v234
	global_load_dwordx4 v[158:161], v[108:109], off
	global_load_dwordx4 v[154:157], v[108:109], off offset:256
	v_lshl_add_u64 v[108:109], v[106:107], 0, v[220:221]
	v_lshlrev_b64 v[216:217], 12, v[214:215]
	v_ashrrev_i32_e32 v211, 31, v210
	v_ashrrev_i32_e32 v205, 31, v204
	global_load_dwordx4 v[150:153], v[108:109], off
	global_load_dwordx4 v[146:149], v[108:109], off offset:256
	v_lshl_add_u64 v[108:109], v[106:107], 0, v[216:217]
	v_lshlrev_b64 v[212:213], 12, v[210:211]
	v_lshlrev_b64 v[208:209], 12, v[204:205]
	global_load_dwordx4 v[142:145], v[108:109], off
	global_load_dwordx4 v[138:141], v[108:109], off offset:256
	v_lshl_add_u64 v[108:109], v[106:107], 0, v[212:213]
	v_lshl_add_u64 v[106:107], v[106:107], 0, v[208:209]
	global_load_dwordx4 v[134:137], v[108:109], off
	global_load_dwordx4 v[122:125], v[108:109], off offset:256
	global_load_dwordx4 v[110:113], v[106:107], off
	s_nop 0
	global_load_dwordx4 v[106:109], v[106:107], off offset:256
	v_pk_mul_f32 v[170:171], v[202:203], v[170:171]
	v_mov_b32_e32 v201, v200
	v_pk_mul_f32 v[172:173], v[200:201], v[172:173]
	v_pk_mul_f32 v[166:167], v[202:203], v[166:167]
	v_pk_mul_f32 v[168:169], v[200:201], v[168:169]
	v_pk_mul_f32 v[130:131], v[202:203], v[130:131]
	v_pk_mul_f32 v[132:133], v[200:201], v[132:133]
	v_pk_mul_f32 v[126:127], v[202:203], v[126:127]
	v_pk_mul_f32 v[128:129], v[200:201], v[128:129]
	s_lshl_b32 s12, s30, 2
	s_ashr_i32 s13, s12, 31
	s_waitcnt vmcnt(0)
	v_lshlrev_b32_e32 v240, 16, v190
	v_add_f32_e32 v240, v170, v240
	v_and_b32_e32 v170, 0xffff0000, v190
	v_add_f32_e32 v190, v171, v170
	v_lshlrev_b32_e32 v170, 16, v191
	v_add_f32_e32 v172, v172, v170
	v_and_b32_e32 v170, 0xffff0000, v191
	v_add_f32_e32 v173, v173, v170
	v_lshlrev_b32_e32 v170, 16, v192
	v_add_f32_e32 v191, v166, v170
	v_and_b32_e32 v166, 0xffff0000, v192
	v_add_f32_e32 v192, v167, v166
	v_lshlrev_b32_e32 v166, 16, v193
	v_add_f32_e32 v241, v168, v166
	v_and_b32_e32 v166, 0xffff0000, v193
	v_lshl_add_u64 v[170:171], s[62:63], 0, v[238:239]
	v_add_f32_e32 v193, v169, v166
	v_cvt_pk_bf16_f32 v166, v240, v190
	v_cvt_pk_bf16_f32 v167, v172, v173
	v_lshl_add_u64 v[170:171], v[170:171], 0, v[236:237]
	v_cvt_pk_bf16_f32 v168, v191, v192
	v_cvt_pk_bf16_f32 v169, v241, v193
	global_store_dwordx4 v[170:171], v[166:169], off
	s_nop 1
	v_mul_f32_e32 v166, v190, v190
	v_mul_f32_e32 v167, v173, v173
	v_fmac_f32_e32 v166, v240, v240
	v_fmac_f32_e32 v167, v172, v172
	v_add_f32_e32 v166, v166, v167
	v_mul_f32_e32 v167, v192, v192
	v_fmac_f32_e32 v167, v191, v191
	v_add_f32_e32 v166, v167, v166
	v_mul_f32_e32 v167, v193, v193
	v_fmac_f32_e32 v167, v241, v241
	v_add_f32_e32 v166, v167, v166
	v_lshlrev_b32_e32 v167, 16, v186
	v_add_f32_e32 v130, v130, v167
	v_and_b32_e32 v167, 0xffff0000, v186
	v_add_f32_e32 v131, v131, v167
	v_lshlrev_b32_e32 v167, 16, v187
	v_add_f32_e32 v132, v132, v167
	v_and_b32_e32 v167, 0xffff0000, v187
	v_add_f32_e32 v133, v133, v167
	v_lshlrev_b32_e32 v167, 16, v188
	v_add_f32_e32 v167, v126, v167
	v_and_b32_e32 v126, 0xffff0000, v188
	v_add_f32_e32 v168, v127, v126
	v_lshlrev_b32_e32 v126, 16, v189
	v_add_f32_e32 v169, v128, v126
	v_and_b32_e32 v126, 0xffff0000, v189
	v_add_f32_e32 v172, v129, v126
	v_cvt_pk_bf16_f32 v126, v130, v131
	v_cvt_pk_bf16_f32 v127, v132, v133
	v_cvt_pk_bf16_f32 v128, v167, v168
	v_cvt_pk_bf16_f32 v129, v169, v172
	global_store_dwordx4 v[170:171], v[126:129], off offset:256
	s_nop 1
	v_mul_f32_e32 v126, v131, v131
	v_mul_f32_e32 v127, v133, v133
	v_fmac_f32_e32 v126, v130, v130
	v_fmac_f32_e32 v127, v132, v132
	v_add_f32_e32 v126, v126, v127
	v_mul_f32_e32 v127, v168, v168
	v_fmac_f32_e32 v127, v167, v167
	v_add_f32_e32 v126, v127, v126
	v_mul_f32_e32 v127, v172, v172
	v_fmac_f32_e32 v127, v169, v169
	v_add_f32_e32 v126, v127, v126
	v_add_f32_e32 v126, v166, v126
	ds_swizzle_b32 v127, v126 offset:swizzle(SWAP,16)
	s_waitcnt lgkmcnt(0)
	v_add_f32_e32 v126, v126, v127
	v_mov_b32_e32 v127, v126
	s_nop 1
	v_permlane32_swap_b32_e32 v126, v127
	s_and_saveexec_b64 s[14:15], s[4:5]
	s_cbranch_execz .LBB0_422
	v_lshlrev_b64 v[128:129], 7, v[234:235]
	v_lshl_add_u64 v[128:129], s[0:1], 0, v[128:129]
	v_lshl_add_u64 v[128:129], s[12:13], 2, v[128:129]
	s_lshl_b32 s30, s50, 2
	v_lshl_add_u64 v[128:129], v[128:129], 0, s[30:31]
	v_add_f32_e32 v126, v126, v127
	global_store_dword v[128:129], v126, off
